# gate|up K-loop: the four per-iteration LDS fragment address adds hoisted to loop-invariant VGPRs (first ds_read of each block no longer waits on a VALU add)
# speedup vs baseline: 1.0067x; 1.0007x over previous
.LBB0_1103:
	s_ashr_i32 s9, s8, 31
	v_cmp_lt_i64_e32 vcc, s[10:11], v[144:145]
	s_lshl_b64 s[10:11], s[8:9], 19
	s_add_u32 s10, s15, s10
	s_addc_u32 s11, s26, s11
	s_and_b64 s[12:13], vcc, exec
	s_cselect_b32 s9, s11, s19
	s_cselect_b32 s42, s10, s18
	s_ashr_i32 s7, s6, 31
	s_lshl_b64 s[12:13], s[6:7], 19
	s_add_u32 s12, s27, s12
	s_addc_u32 s13, s28, s13
	s_and_b64 s[24:25], vcc, exec
	s_cselect_b32 s7, s13, s23
	s_cselect_b32 s43, s12, s22
	s_add_u32 s18, s18, 0x40080
	s_addc_u32 s19, s19, 0
	s_add_u32 s44, s22, 0x100
	v_mov_b32_e32 v0, 0
	s_addc_u32 s45, s23, 0
	s_mov_b32 s46, -2
	v_mov_b32_e32 v1, v0
	v_mov_b64_e32 v[2:3], 0
	v_mov_b64_e32 v[4:5], 0
	v_mov_b64_e32 v[6:7], 0
	v_mov_b64_e32 v[8:9], 0
	v_mov_b64_e32 v[10:11], 0
	v_mov_b64_e32 v[12:13], 0
	v_mov_b64_e32 v[14:15], 0
	v_mov_b64_e32 v[16:17], 0
	v_mov_b64_e32 v[18:19], 0
	v_mov_b64_e32 v[20:21], 0
	v_mov_b64_e32 v[22:23], 0
	v_mov_b64_e32 v[24:25], 0
	v_mov_b64_e32 v[26:27], 0
	v_mov_b64_e32 v[28:29], 0
	v_mov_b64_e32 v[30:31], 0
	v_mov_b64_e32 v[32:33], 0
	v_mov_b64_e32 v[34:35], 0
	v_mov_b64_e32 v[36:37], 0
	v_mov_b64_e32 v[38:39], 0
	v_mov_b64_e32 v[40:41], 0
	v_mov_b64_e32 v[42:43], 0
	v_mov_b64_e32 v[44:45], 0
	v_mov_b64_e32 v[46:47], 0
	v_mov_b64_e32 v[48:49], 0
	v_mov_b64_e32 v[50:51], 0
	v_mov_b64_e32 v[52:53], 0
	v_mov_b64_e32 v[54:55], 0
	v_mov_b64_e32 v[56:57], 0
	v_mov_b64_e32 v[58:59], 0
	v_mov_b64_e32 v[60:61], 0
	v_mov_b64_e32 v[62:63], 0
	v_mov_b64_e32 v[64:65], 0
	v_mov_b64_e32 v[66:67], 0
	v_mov_b64_e32 v[68:69], 0
	v_mov_b64_e32 v[70:71], 0
	v_mov_b64_e32 v[72:73], 0
	v_mov_b64_e32 v[74:75], 0
	v_mov_b64_e32 v[76:77], 0
	v_mov_b64_e32 v[78:79], 0
	v_mov_b64_e32 v[80:81], 0
	v_mov_b64_e32 v[82:83], 0
	v_mov_b64_e32 v[84:85], 0
	v_mov_b64_e32 v[86:87], 0
	v_mov_b64_e32 v[88:89], 0
	v_mov_b64_e32 v[90:91], 0
	v_mov_b64_e32 v[92:93], 0
	v_mov_b64_e32 v[94:95], 0
	v_mov_b64_e32 v[96:97], 0
	v_mov_b64_e32 v[98:99], 0
	v_mov_b64_e32 v[100:101], 0
	v_mov_b64_e32 v[102:103], 0
	v_mov_b64_e32 v[104:105], 0
	v_mov_b64_e32 v[106:107], 0
	v_mov_b64_e32 v[108:109], 0
	v_mov_b64_e32 v[110:111], 0
	v_mov_b64_e32 v[112:113], 0
	v_mov_b64_e32 v[114:115], 0
	v_mov_b64_e32 v[116:117], 0
	v_mov_b64_e32 v[118:119], 0
	v_mov_b64_e32 v[120:121], 0
	v_mov_b64_e32 v[122:123], 0
	v_mov_b64_e32 v[124:125], 0
	v_mov_b64_e32 v[126:127], 0
	v_add_u32_e32 v250, 0x14000, v154
	v_add_u32_e32 v251, 0x18000, v154
	v_add_u32_e32 v252, 0x1c000, v154
	v_add_u32_e32 v253, 0x10000, v154
	v_add_u32_e32 v168, 0x10000, v154
	ds_read_b128 v[156:159], v168
	ds_read_b128 v[160:163], v168 offset:1024
	ds_read_b128 v[164:167], v168 offset:2048
	ds_read_b128 v[168:171], v168 offset:3072
.LBB0_1104:
	s_add_u32 s22, s18, 0xfffc0080
	s_addc_u32 s23, s19, -1
	s_add_i32 s47, 0, 0x10000
	s_cmp_eq_u32 s46, 12
	s_cselect_b32 s25, s9, s23
	s_cselect_b32 s24, s42, s22
	s_cselect_b32 s23, s7, s45
	s_cselect_b32 s22, s43, s44
	s_add_i32 m0, s17, 0xc000
	ds_read_b128 v[172:175], v155
	ds_read_b128 v[180:183], v155 offset:2048
	ds_read_b128 v[188:191], v155 offset:4096
	ds_read_b128 v[220:223], v155 offset:6144
	ds_read_b128 v[176:179], v155 offset:1024
	ds_read_b128 v[184:187], v155 offset:3072
	ds_read_b128 v[216:219], v155 offset:5120
	ds_read_b128 v[224:227], v155 offset:7168
	global_load_lds_dwordx4 v130, s[18:19]
	s_add_i32 m0, s17, 0xe000
	s_nop 0
	global_load_lds_dwordx4 v150, s[18:19]
	s_waitcnt lgkmcnt(8)
	s_waitcnt vmcnt(10)
	s_barrier
	s_waitcnt lgkmcnt(4)
	v_mfma_f32_16x16x32_bf16 v[124:127], v[156:159], v[172:175], v[124:127]
	v_mfma_f32_16x16x32_bf16 v[120:123], v[164:167], v[172:175], v[120:123]
	v_mfma_f32_16x16x32_bf16 v[108:111], v[156:159], v[180:183], v[108:111]
	v_mfma_f32_16x16x32_bf16 v[104:107], v[164:167], v[180:183], v[104:107]
	v_mfma_f32_16x16x32_bf16 v[92:95], v[156:159], v[188:191], v[92:95]
	v_mfma_f32_16x16x32_bf16 v[88:91], v[164:167], v[188:191], v[88:91]
	v_mfma_f32_16x16x32_bf16 v[76:79], v[156:159], v[220:223], v[76:79]
	v_mfma_f32_16x16x32_bf16 v[72:75], v[164:167], v[220:223], v[72:75]
	s_waitcnt lgkmcnt(0)
	v_mfma_f32_16x16x32_bf16 v[124:127], v[160:163], v[176:179], v[124:127]
	v_mfma_f32_16x16x32_bf16 v[120:123], v[168:171], v[176:179], v[120:123]
	v_mfma_f32_16x16x32_bf16 v[108:111], v[160:163], v[184:187], v[108:111]
	v_mfma_f32_16x16x32_bf16 v[104:107], v[168:171], v[184:187], v[104:107]
	v_mfma_f32_16x16x32_bf16 v[92:95], v[160:163], v[216:219], v[92:95]
	v_mfma_f32_16x16x32_bf16 v[88:91], v[168:171], v[216:219], v[88:91]
	v_mfma_f32_16x16x32_bf16 v[76:79], v[160:163], v[224:227], v[76:79]
	v_mfma_f32_16x16x32_bf16 v[72:75], v[168:171], v[224:227], v[72:75]
	s_barrier
	s_add_i32 s50, 0, 0x14000
	s_add_i32 s47, s47, s29
	ds_read_b128 v[228:231], v250
	ds_read_b128 v[236:239], v250 offset:2048
	ds_read_b128 v[232:235], v250 offset:1024
	ds_read_b128 v[240:243], v250 offset:3072
	s_mov_b32 m0, s47
	s_nop 0
	global_load_lds_dwordx4 v132, s[22:23]
	s_add_i32 m0, s47, 0x2000
	s_nop 0
	global_load_lds_dwordx4 v128, s[22:23]
	s_waitcnt vmcnt(10)
	s_barrier
	s_waitcnt lgkmcnt(2)
	v_mfma_f32_16x16x32_bf16 v[116:119], v[228:231], v[172:175], v[116:119]
	v_mfma_f32_16x16x32_bf16 v[112:115], v[236:239], v[172:175], v[112:115]
	v_mfma_f32_16x16x32_bf16 v[100:103], v[228:231], v[180:183], v[100:103]
	v_mfma_f32_16x16x32_bf16 v[96:99], v[236:239], v[180:183], v[96:99]
	v_mfma_f32_16x16x32_bf16 v[84:87], v[228:231], v[188:191], v[84:87]
	v_mfma_f32_16x16x32_bf16 v[80:83], v[236:239], v[188:191], v[80:83]
	v_mfma_f32_16x16x32_bf16 v[68:71], v[228:231], v[220:223], v[68:71]
	v_mfma_f32_16x16x32_bf16 v[64:67], v[236:239], v[220:223], v[64:67]
	s_waitcnt lgkmcnt(0)
	v_mfma_f32_16x16x32_bf16 v[116:119], v[232:235], v[176:179], v[116:119]
	v_mfma_f32_16x16x32_bf16 v[112:115], v[240:243], v[176:179], v[112:115]
	v_mfma_f32_16x16x32_bf16 v[100:103], v[232:235], v[184:187], v[100:103]
	v_mfma_f32_16x16x32_bf16 v[96:99], v[240:243], v[184:187], v[96:99]
	v_mfma_f32_16x16x32_bf16 v[84:87], v[232:235], v[216:219], v[84:87]
	v_mfma_f32_16x16x32_bf16 v[80:83], v[240:243], v[216:219], v[80:83]
	v_mfma_f32_16x16x32_bf16 v[68:71], v[232:235], v[224:227], v[68:71]
	v_mfma_f32_16x16x32_bf16 v[64:67], v[240:243], v[224:227], v[64:67]
	s_mov_b32 m0, s17
	v_lshl_add_u64 v[246:247], s[24:25], 0, v[132:133]
	s_barrier
	ds_read_b128 v[172:175], v155 offset:16384
	ds_read_b128 v[180:183], v155 offset:18432
	ds_read_b128 v[188:191], v155 offset:20480
	ds_read_b128 v[220:223], v155 offset:22528
	ds_read_b128 v[176:179], v155 offset:17408
	ds_read_b128 v[184:187], v155 offset:19456
	ds_read_b128 v[216:219], v155 offset:21504
	ds_read_b128 v[224:227], v155 offset:23552
	global_load_lds_dwordx4 v132, s[24:25]
	v_lshl_add_u64 v[248:249], s[24:25], 0, v[128:129]
	s_mov_b32 m0, s31
	s_nop 0
	global_load_lds_dwordx4 v128, s[24:25]
	s_waitcnt vmcnt(10)
	s_barrier
	s_waitcnt lgkmcnt(4)
	v_mfma_f32_16x16x32_bf16 v[60:63], v[156:159], v[172:175], v[60:63]
	v_mfma_f32_16x16x32_bf16 v[56:59], v[164:167], v[172:175], v[56:59]
	v_mfma_f32_16x16x32_bf16 v[44:47], v[156:159], v[180:183], v[44:47]
	v_mfma_f32_16x16x32_bf16 v[40:43], v[164:167], v[180:183], v[40:43]
	v_mfma_f32_16x16x32_bf16 v[28:31], v[156:159], v[188:191], v[28:31]
	v_mfma_f32_16x16x32_bf16 v[24:27], v[164:167], v[188:191], v[24:27]
	v_mfma_f32_16x16x32_bf16 v[12:15], v[156:159], v[220:223], v[12:15]
	v_mfma_f32_16x16x32_bf16 v[8:11], v[164:167], v[220:223], v[8:11]
	s_waitcnt lgkmcnt(0)
	v_mfma_f32_16x16x32_bf16 v[60:63], v[160:163], v[176:179], v[60:63]
	v_mfma_f32_16x16x32_bf16 v[56:59], v[168:171], v[176:179], v[56:59]
	v_mfma_f32_16x16x32_bf16 v[44:47], v[160:163], v[184:187], v[44:47]
	v_mfma_f32_16x16x32_bf16 v[40:43], v[168:171], v[184:187], v[40:43]
	v_mfma_f32_16x16x32_bf16 v[28:31], v[160:163], v[216:219], v[28:31]
	v_mfma_f32_16x16x32_bf16 v[24:27], v[168:171], v[216:219], v[24:27]
	v_mfma_f32_16x16x32_bf16 v[12:15], v[160:163], v[224:227], v[12:15]
	v_mfma_f32_16x16x32_bf16 v[8:11], v[168:171], v[224:227], v[8:11]
	s_barrier
	s_add_u32 s48, s22, 0x40000
	s_addc_u32 s49, s23, 0
	s_add_i32 s47, s50, s29
	s_mov_b32 m0, s47
	s_nop 0
	global_load_lds_dwordx4 v132, s[48:49]
	s_add_i32 m0, s47, 0x2000
	s_nop 0
	global_load_lds_dwordx4 v128, s[48:49]
	ds_read_b128 v[156:159], v251
	ds_read_b128 v[160:163], v251 offset:1024
	ds_read_b128 v[164:167], v251 offset:2048
	ds_read_b128 v[168:171], v251 offset:3072
	s_waitcnt vmcnt(10)
	s_barrier
	v_mfma_f32_16x16x32_bf16 v[52:55], v[228:231], v[172:175], v[52:55]
	v_mfma_f32_16x16x32_bf16 v[48:51], v[236:239], v[172:175], v[48:51]
	v_mfma_f32_16x16x32_bf16 v[36:39], v[228:231], v[180:183], v[36:39]
	v_mfma_f32_16x16x32_bf16 v[32:35], v[236:239], v[180:183], v[32:35]
	v_mfma_f32_16x16x32_bf16 v[20:23], v[228:231], v[188:191], v[20:23]
	v_mfma_f32_16x16x32_bf16 v[16:19], v[236:239], v[188:191], v[16:19]
	v_mfma_f32_16x16x32_bf16 v[4:7], v[228:231], v[220:223], v[4:7]
	v_mfma_f32_16x16x32_bf16 v[0:3], v[236:239], v[220:223], v[0:3]
	v_mfma_f32_16x16x32_bf16 v[52:55], v[232:235], v[176:179], v[52:55]
	v_mfma_f32_16x16x32_bf16 v[48:51], v[240:243], v[176:179], v[48:51]
	v_mfma_f32_16x16x32_bf16 v[36:39], v[232:235], v[184:187], v[36:39]
	v_mfma_f32_16x16x32_bf16 v[32:35], v[240:243], v[184:187], v[32:35]
	v_mfma_f32_16x16x32_bf16 v[20:23], v[232:235], v[216:219], v[20:23]
	v_mfma_f32_16x16x32_bf16 v[16:19], v[240:243], v[216:219], v[16:19]
	v_mfma_f32_16x16x32_bf16 v[4:7], v[232:235], v[224:227], v[4:7]
	v_mfma_f32_16x16x32_bf16 v[0:3], v[240:243], v[224:227], v[0:3]
	s_add_i32 s47, 0, 0x18000
	s_barrier
	s_add_u32 s24, s24, 0x40000
	s_addc_u32 s25, s25, 0
	s_mov_b32 m0, s34
	ds_read_b128 v[172:175], v155 offset:32768
	ds_read_b128 v[180:183], v155 offset:34816
	ds_read_b128 v[188:191], v155 offset:36864
	ds_read_b128 v[220:223], v155 offset:38912
	ds_read_b128 v[176:179], v155 offset:33792
	ds_read_b128 v[184:187], v155 offset:35840
	ds_read_b128 v[216:219], v155 offset:37888
	ds_read_b128 v[224:227], v155 offset:39936
	global_load_lds_dwordx4 v132, s[24:25]
	s_mov_b32 m0, s35
	s_nop 0
	global_load_lds_dwordx4 v128, s[24:25]
	s_waitcnt lgkmcnt(8)
	s_waitcnt vmcnt(10)
	s_barrier
	s_waitcnt lgkmcnt(4)
	v_mfma_f32_16x16x32_bf16 v[124:127], v[156:159], v[172:175], v[124:127]
	v_mfma_f32_16x16x32_bf16 v[120:123], v[164:167], v[172:175], v[120:123]
	v_mfma_f32_16x16x32_bf16 v[108:111], v[156:159], v[180:183], v[108:111]
	v_mfma_f32_16x16x32_bf16 v[104:107], v[164:167], v[180:183], v[104:107]
	v_mfma_f32_16x16x32_bf16 v[92:95], v[156:159], v[188:191], v[92:95]
	v_mfma_f32_16x16x32_bf16 v[88:91], v[164:167], v[188:191], v[88:91]
	v_mfma_f32_16x16x32_bf16 v[76:79], v[156:159], v[220:223], v[76:79]
	v_mfma_f32_16x16x32_bf16 v[72:75], v[164:167], v[220:223], v[72:75]
	s_waitcnt lgkmcnt(0)
	v_mfma_f32_16x16x32_bf16 v[124:127], v[160:163], v[176:179], v[124:127]
	v_mfma_f32_16x16x32_bf16 v[120:123], v[168:171], v[176:179], v[120:123]
	v_mfma_f32_16x16x32_bf16 v[108:111], v[160:163], v[184:187], v[108:111]
	v_mfma_f32_16x16x32_bf16 v[104:107], v[168:171], v[184:187], v[104:107]
	v_mfma_f32_16x16x32_bf16 v[92:95], v[160:163], v[216:219], v[92:95]
	v_mfma_f32_16x16x32_bf16 v[88:91], v[168:171], v[216:219], v[88:91]
	v_mfma_f32_16x16x32_bf16 v[76:79], v[160:163], v[224:227], v[76:79]
	v_mfma_f32_16x16x32_bf16 v[72:75], v[168:171], v[224:227], v[72:75]
	s_barrier
	s_add_i32 s24, 0, 0x1c000
	s_add_i32 s25, s47, s29
	s_mov_b32 m0, s25
	ds_read_b128 v[228:231], v252
	ds_read_b128 v[236:239], v252 offset:2048
	ds_read_b128 v[232:235], v252 offset:1024
	ds_read_b128 v[240:243], v252 offset:3072
	s_add_u32 s98, s22, 0x80
	s_addc_u32 s99, s23, 0
	global_load_lds_dwordx4 v132, s[98:99]
	s_add_i32 m0, s25, 0x2000
	s_nop 0
	global_load_lds_dwordx4 v128, s[98:99]
	s_waitcnt vmcnt(10)
	s_barrier
	s_waitcnt lgkmcnt(2)
	v_mfma_f32_16x16x32_bf16 v[116:119], v[228:231], v[172:175], v[116:119]
	v_mfma_f32_16x16x32_bf16 v[112:115], v[236:239], v[172:175], v[112:115]
	v_mfma_f32_16x16x32_bf16 v[100:103], v[228:231], v[180:183], v[100:103]
	v_mfma_f32_16x16x32_bf16 v[96:99], v[236:239], v[180:183], v[96:99]
	v_mfma_f32_16x16x32_bf16 v[84:87], v[228:231], v[188:191], v[84:87]
	v_mfma_f32_16x16x32_bf16 v[80:83], v[236:239], v[188:191], v[80:83]
	v_mfma_f32_16x16x32_bf16 v[68:71], v[228:231], v[220:223], v[68:71]
	v_mfma_f32_16x16x32_bf16 v[64:67], v[236:239], v[220:223], v[64:67]
	s_waitcnt lgkmcnt(0)
	v_mfma_f32_16x16x32_bf16 v[116:119], v[232:235], v[176:179], v[116:119]
	v_mfma_f32_16x16x32_bf16 v[112:115], v[240:243], v[176:179], v[112:115]
	v_mfma_f32_16x16x32_bf16 v[100:103], v[232:235], v[184:187], v[100:103]
	v_mfma_f32_16x16x32_bf16 v[96:99], v[240:243], v[184:187], v[96:99]
	v_mfma_f32_16x16x32_bf16 v[84:87], v[232:235], v[216:219], v[84:87]
	v_mfma_f32_16x16x32_bf16 v[80:83], v[240:243], v[216:219], v[80:83]
	v_mfma_f32_16x16x32_bf16 v[68:71], v[232:235], v[224:227], v[68:71]
	v_mfma_f32_16x16x32_bf16 v[64:67], v[240:243], v[224:227], v[64:67]
	s_mov_b32 m0, s36
	v_lshl_add_u64 v[152:153], v[246:247], 0, s[66:67]
	s_barrier
	ds_read_b128 v[172:175], v155 offset:49152
	ds_read_b128 v[180:183], v155 offset:51200
	ds_read_b128 v[188:191], v155 offset:53248
	ds_read_b128 v[220:223], v155 offset:55296
	ds_read_b128 v[176:179], v155 offset:50176
	ds_read_b128 v[184:187], v155 offset:52224
	ds_read_b128 v[216:219], v155 offset:54272
	ds_read_b128 v[224:227], v155 offset:56320
	global_load_lds_dwordx4 v[152:153], off
	v_lshl_add_u64 v[152:153], v[248:249], 0, s[66:67]
	s_mov_b32 m0, s37
	s_nop 0
	global_load_lds_dwordx4 v[152:153], off
	s_waitcnt vmcnt(10)
	s_barrier
	s_waitcnt lgkmcnt(4)
	v_mfma_f32_16x16x32_bf16 v[60:63], v[156:159], v[172:175], v[60:63]
	v_mfma_f32_16x16x32_bf16 v[56:59], v[164:167], v[172:175], v[56:59]
	v_mfma_f32_16x16x32_bf16 v[44:47], v[156:159], v[180:183], v[44:47]
	v_mfma_f32_16x16x32_bf16 v[40:43], v[164:167], v[180:183], v[40:43]
	v_mfma_f32_16x16x32_bf16 v[28:31], v[156:159], v[188:191], v[28:31]
	v_mfma_f32_16x16x32_bf16 v[24:27], v[164:167], v[188:191], v[24:27]
	v_mfma_f32_16x16x32_bf16 v[12:15], v[156:159], v[220:223], v[12:15]
	v_mfma_f32_16x16x32_bf16 v[8:11], v[164:167], v[220:223], v[8:11]
	s_waitcnt lgkmcnt(0)
	v_mfma_f32_16x16x32_bf16 v[60:63], v[160:163], v[176:179], v[60:63]
	v_mfma_f32_16x16x32_bf16 v[56:59], v[168:171], v[176:179], v[56:59]
	v_mfma_f32_16x16x32_bf16 v[44:47], v[160:163], v[184:187], v[44:47]
	v_mfma_f32_16x16x32_bf16 v[40:43], v[168:171], v[184:187], v[40:43]
	v_mfma_f32_16x16x32_bf16 v[28:31], v[160:163], v[216:219], v[28:31]
	v_mfma_f32_16x16x32_bf16 v[24:27], v[168:171], v[216:219], v[24:27]
	v_mfma_f32_16x16x32_bf16 v[12:15], v[160:163], v[224:227], v[12:15]
	v_mfma_f32_16x16x32_bf16 v[8:11], v[168:171], v[224:227], v[8:11]
	s_barrier
	s_add_u32 s22, s22, 0x40080
	s_addc_u32 s23, s23, 0
	s_add_i32 s24, s24, s29
	s_mov_b32 m0, s24
	s_nop 0
	global_load_lds_dwordx4 v132, s[22:23]
	s_add_i32 m0, s24, 0x2000
	s_nop 0
	global_load_lds_dwordx4 v128, s[22:23]
	ds_read_b128 v[156:159], v253
	ds_read_b128 v[160:163], v253 offset:1024
	ds_read_b128 v[164:167], v253 offset:2048
	ds_read_b128 v[168:171], v253 offset:3072
	s_waitcnt vmcnt(10)
	s_barrier
	v_mfma_f32_16x16x32_bf16 v[52:55], v[228:231], v[172:175], v[52:55]
	v_mfma_f32_16x16x32_bf16 v[48:51], v[236:239], v[172:175], v[48:51]
	v_mfma_f32_16x16x32_bf16 v[36:39], v[228:231], v[180:183], v[36:39]
	v_mfma_f32_16x16x32_bf16 v[32:35], v[236:239], v[180:183], v[32:35]
	v_mfma_f32_16x16x32_bf16 v[20:23], v[228:231], v[188:191], v[20:23]
	v_mfma_f32_16x16x32_bf16 v[16:19], v[236:239], v[188:191], v[16:19]
	v_mfma_f32_16x16x32_bf16 v[4:7], v[228:231], v[220:223], v[4:7]
	v_mfma_f32_16x16x32_bf16 v[0:3], v[236:239], v[220:223], v[0:3]
	v_mfma_f32_16x16x32_bf16 v[52:55], v[232:235], v[176:179], v[52:55]
	v_mfma_f32_16x16x32_bf16 v[48:51], v[240:243], v[176:179], v[48:51]
	v_mfma_f32_16x16x32_bf16 v[36:39], v[232:235], v[184:187], v[36:39]
	v_mfma_f32_16x16x32_bf16 v[32:35], v[240:243], v[184:187], v[32:35]
	v_mfma_f32_16x16x32_bf16 v[20:23], v[232:235], v[216:219], v[20:23]
	v_mfma_f32_16x16x32_bf16 v[16:19], v[240:243], v[216:219], v[16:19]
	v_mfma_f32_16x16x32_bf16 v[4:7], v[232:235], v[224:227], v[4:7]
	v_mfma_f32_16x16x32_bf16 v[0:3], v[240:243], v[224:227], v[0:3]
	s_add_i32 s46, s46, 2
	s_add_u32 s18, s18, 0x100
	s_addc_u32 s19, s19, 0
	s_add_u32 s44, s44, 0x100
	s_addc_u32 s45, s45, 0
	s_cmp_gt_u32 s46, 13
	s_barrier
	s_cbranch_scc0 .LBB0_1104
	s_waitcnt lgkmcnt(0)
	v_mov_b32_e32 v153, v135
	s_mov_b64 s[18:19], s[0:1]
	s_load_dwordx2 s[18:19], s[18:19], 0x88
	s_nop 0
	v_readfirstlane_b32 s7, v153
	s_ashr_i32 s9, s7, 2
	s_lshr_b32 s7, s7, 1
	s_lshl_b32 s22, s41, 7
	s_and_b32 s7, s7, 0x60
	s_andn2_b32 s9, s9, 63
	s_or_b32 s7, s7, s22
	v_lshrrev_b32_e32 v152, 1, v153
	v_and_or_b32 v152, v152, 24, s7
	v_and_or_b32 v153, v153, 15, s9
	v_lshl_add_u32 v156, s16, 8, v153
	v_ashrrev_i32_e32 v153, 31, v152
	v_mov_b32_e32 v168, 0xbfb8aa3b
	v_mov_b32_e32 v169, 0xbfb8aa3b
	v_mov_b32_e32 v170, 1.0
	v_mov_b32_e32 v171, 1.0
	v_pk_mul_f32 v[160:161], v[124:125], v[168:169]
	v_pk_mul_f32 v[162:163], v[126:127], v[168:169]
	v_pk_mul_f32 v[164:165], v[116:117], v[168:169]
	v_pk_mul_f32 v[166:167], v[118:119], v[168:169]
	v_exp_f32_e32 v160, v160
	v_exp_f32_e32 v161, v161
	v_exp_f32_e32 v162, v162
	v_exp_f32_e32 v163, v163
	v_exp_f32_e32 v164, v164
	v_exp_f32_e32 v165, v165
	v_exp_f32_e32 v166, v166
	v_exp_f32_e32 v167, v167
	s_waitcnt lgkmcnt(0)
	v_lshl_add_u64 v[152:153], v[152:153], 1, s[18:19]
	s_mov_b64 s[18:19], 0xa2a4400
	v_lshl_add_u64 v[152:153], v[152:153], 0, s[18:19]
	s_and_b64 vcc, exec, s[4:5]
	s_mov_b32 s41, s6
	s_mov_b32 s16, s8
	s_mov_b64 s[22:23], s[12:13]
	v_pk_add_f32 v[160:161], v[160:161], v[170:171]
	v_pk_add_f32 v[162:163], v[162:163], v[170:171]
	v_pk_add_f32 v[164:165], v[164:165], v[170:171]
	v_pk_add_f32 v[166:167], v[166:167], v[170:171]
	v_rcp_f32_e32 v160, v160
	v_rcp_f32_e32 v161, v161
	v_rcp_f32_e32 v162, v162
	v_rcp_f32_e32 v163, v163
	v_rcp_f32_e32 v164, v164
	v_rcp_f32_e32 v165, v165
	v_rcp_f32_e32 v166, v166
	v_rcp_f32_e32 v167, v167
	v_mov_b32_e32 v158, v156
	v_mad_i64_i32 v[158:159], s[18:19], v158, s73, v[152:153]
	v_pk_mul_f32 v[124:125], v[124:125], v[160:161]
	v_pk_mul_f32 v[126:127], v[126:127], v[162:163]
	v_pk_mul_f32 v[116:117], v[116:117], v[164:165]
	v_pk_mul_f32 v[118:119], v[118:119], v[166:167]
	v_pk_mul_f32 v[120:121], v[120:121], v[124:125]
	v_pk_mul_f32 v[122:123], v[122:123], v[126:127]
	v_pk_mul_f32 v[112:113], v[112:113], v[116:117]
	v_pk_mul_f32 v[114:115], v[114:115], v[118:119]
	v_cvt_pk_bf16_f32 v120, v120, v121
	v_cvt_pk_bf16_f32 v121, v122, v123
	v_cvt_pk_bf16_f32 v122, v112, v113
	v_cvt_pk_bf16_f32 v123, v114, v115
	global_store_dwordx4 v[158:159], v[120:123], off sc1
	v_pk_mul_f32 v[160:161], v[108:109], v[168:169]
	v_pk_mul_f32 v[162:163], v[110:111], v[168:169]
	v_pk_mul_f32 v[164:165], v[100:101], v[168:169]
	v_pk_mul_f32 v[166:167], v[102:103], v[168:169]
	v_exp_f32_e32 v160, v160
	v_exp_f32_e32 v161, v161
	v_exp_f32_e32 v162, v162
	v_exp_f32_e32 v163, v163
	v_exp_f32_e32 v164, v164
	v_exp_f32_e32 v165, v165
	v_exp_f32_e32 v166, v166
	v_exp_f32_e32 v167, v167
	v_pk_add_f32 v[160:161], v[160:161], v[170:171]
	v_pk_add_f32 v[162:163], v[162:163], v[170:171]
	v_pk_add_f32 v[164:165], v[164:165], v[170:171]
	v_pk_add_f32 v[166:167], v[166:167], v[170:171]
	v_rcp_f32_e32 v160, v160
	v_rcp_f32_e32 v161, v161
	v_rcp_f32_e32 v162, v162
	v_rcp_f32_e32 v163, v163
	v_rcp_f32_e32 v164, v164
	v_rcp_f32_e32 v165, v165
	v_rcp_f32_e32 v166, v166
	v_rcp_f32_e32 v167, v167
	v_add_u32_e32 v158, 0x10, v156
	v_mad_i64_i32 v[158:159], s[18:19], v158, s73, v[152:153]
	v_pk_mul_f32 v[108:109], v[108:109], v[160:161]
	v_pk_mul_f32 v[110:111], v[110:111], v[162:163]
	v_pk_mul_f32 v[100:101], v[100:101], v[164:165]
	v_pk_mul_f32 v[102:103], v[102:103], v[166:167]
	v_pk_mul_f32 v[104:105], v[104:105], v[108:109]
	v_pk_mul_f32 v[106:107], v[106:107], v[110:111]
	v_pk_mul_f32 v[96:97], v[96:97], v[100:101]
	v_pk_mul_f32 v[98:99], v[98:99], v[102:103]
	v_cvt_pk_bf16_f32 v104, v104, v105
	v_cvt_pk_bf16_f32 v105, v106, v107
	v_cvt_pk_bf16_f32 v106, v96, v97
	v_cvt_pk_bf16_f32 v107, v98, v99
	global_store_dwordx4 v[158:159], v[104:107], off sc1
	v_pk_mul_f32 v[160:161], v[92:93], v[168:169]
	v_pk_mul_f32 v[162:163], v[94:95], v[168:169]
	v_pk_mul_f32 v[164:165], v[84:85], v[168:169]
	v_pk_mul_f32 v[166:167], v[86:87], v[168:169]
	v_exp_f32_e32 v160, v160
	v_exp_f32_e32 v161, v161
	v_exp_f32_e32 v162, v162
	v_exp_f32_e32 v163, v163
	v_exp_f32_e32 v164, v164
	v_exp_f32_e32 v165, v165
	v_exp_f32_e32 v166, v166
	v_exp_f32_e32 v167, v167
	v_pk_add_f32 v[160:161], v[160:161], v[170:171]
	v_pk_add_f32 v[162:163], v[162:163], v[170:171]
	v_pk_add_f32 v[164:165], v[164:165], v[170:171]
	v_pk_add_f32 v[166:167], v[166:167], v[170:171]
	v_rcp_f32_e32 v160, v160
	v_rcp_f32_e32 v161, v161
	v_rcp_f32_e32 v162, v162
	v_rcp_f32_e32 v163, v163
	v_rcp_f32_e32 v164, v164
	v_rcp_f32_e32 v165, v165
	v_rcp_f32_e32 v166, v166
	v_rcp_f32_e32 v167, v167
	v_add_u32_e32 v158, 0x20, v156
	v_mad_i64_i32 v[158:159], s[18:19], v158, s73, v[152:153]
	v_pk_mul_f32 v[92:93], v[92:93], v[160:161]
	v_pk_mul_f32 v[94:95], v[94:95], v[162:163]
	v_pk_mul_f32 v[84:85], v[84:85], v[164:165]
	v_pk_mul_f32 v[86:87], v[86:87], v[166:167]
	v_pk_mul_f32 v[88:89], v[88:89], v[92:93]
	v_pk_mul_f32 v[90:91], v[90:91], v[94:95]
	v_pk_mul_f32 v[80:81], v[80:81], v[84:85]
	v_pk_mul_f32 v[82:83], v[82:83], v[86:87]
	v_cvt_pk_bf16_f32 v88, v88, v89
	v_cvt_pk_bf16_f32 v89, v90, v91
	v_cvt_pk_bf16_f32 v90, v80, v81
	v_cvt_pk_bf16_f32 v91, v82, v83
	global_store_dwordx4 v[158:159], v[88:91], off sc1
	v_pk_mul_f32 v[160:161], v[76:77], v[168:169]
	v_pk_mul_f32 v[162:163], v[78:79], v[168:169]
	v_pk_mul_f32 v[164:165], v[68:69], v[168:169]
	v_pk_mul_f32 v[166:167], v[70:71], v[168:169]
	v_exp_f32_e32 v160, v160
	v_exp_f32_e32 v161, v161
	v_exp_f32_e32 v162, v162
	v_exp_f32_e32 v163, v163
	v_exp_f32_e32 v164, v164
	v_exp_f32_e32 v165, v165
	v_exp_f32_e32 v166, v166
	v_exp_f32_e32 v167, v167
	v_pk_add_f32 v[160:161], v[160:161], v[170:171]
	v_pk_add_f32 v[162:163], v[162:163], v[170:171]
	v_pk_add_f32 v[164:165], v[164:165], v[170:171]
	v_pk_add_f32 v[166:167], v[166:167], v[170:171]
	v_rcp_f32_e32 v160, v160
	v_rcp_f32_e32 v161, v161
	v_rcp_f32_e32 v162, v162
	v_rcp_f32_e32 v163, v163
	v_rcp_f32_e32 v164, v164
	v_rcp_f32_e32 v165, v165
	v_rcp_f32_e32 v166, v166
	v_rcp_f32_e32 v167, v167
	v_add_u32_e32 v158, 0x30, v156
	v_mad_i64_i32 v[158:159], s[18:19], v158, s73, v[152:153]
	v_pk_mul_f32 v[76:77], v[76:77], v[160:161]
	v_pk_mul_f32 v[78:79], v[78:79], v[162:163]
	v_pk_mul_f32 v[68:69], v[68:69], v[164:165]
	v_pk_mul_f32 v[70:71], v[70:71], v[166:167]
	v_pk_mul_f32 v[72:73], v[72:73], v[76:77]
	v_pk_mul_f32 v[74:75], v[74:75], v[78:79]
	v_pk_mul_f32 v[64:65], v[64:65], v[68:69]
	v_pk_mul_f32 v[66:67], v[66:67], v[70:71]
	v_cvt_pk_bf16_f32 v72, v72, v73
	v_cvt_pk_bf16_f32 v73, v74, v75
	v_cvt_pk_bf16_f32 v74, v64, v65
	v_cvt_pk_bf16_f32 v75, v66, v67
	global_store_dwordx4 v[158:159], v[72:75], off sc1
	v_pk_mul_f32 v[160:161], v[60:61], v[168:169]
	v_pk_mul_f32 v[162:163], v[62:63], v[168:169]
	v_pk_mul_f32 v[164:165], v[52:53], v[168:169]
	v_pk_mul_f32 v[166:167], v[54:55], v[168:169]
	v_exp_f32_e32 v160, v160
	v_exp_f32_e32 v161, v161
	v_exp_f32_e32 v162, v162
	v_exp_f32_e32 v163, v163
	v_exp_f32_e32 v164, v164
	v_exp_f32_e32 v165, v165
	v_exp_f32_e32 v166, v166
	v_exp_f32_e32 v167, v167
	v_pk_add_f32 v[160:161], v[160:161], v[170:171]
	v_pk_add_f32 v[162:163], v[162:163], v[170:171]
	v_pk_add_f32 v[164:165], v[164:165], v[170:171]
	v_pk_add_f32 v[166:167], v[166:167], v[170:171]
	v_rcp_f32_e32 v160, v160
	v_rcp_f32_e32 v161, v161
	v_rcp_f32_e32 v162, v162
	v_rcp_f32_e32 v163, v163
	v_rcp_f32_e32 v164, v164
	v_rcp_f32_e32 v165, v165
	v_rcp_f32_e32 v166, v166
	v_rcp_f32_e32 v167, v167
	v_add_u32_e32 v158, 0x80, v156
	v_mad_i64_i32 v[158:159], s[18:19], v158, s73, v[152:153]
	v_pk_mul_f32 v[60:61], v[60:61], v[160:161]
	v_pk_mul_f32 v[62:63], v[62:63], v[162:163]
	v_pk_mul_f32 v[52:53], v[52:53], v[164:165]
	v_pk_mul_f32 v[54:55], v[54:55], v[166:167]
	v_pk_mul_f32 v[56:57], v[56:57], v[60:61]
	v_pk_mul_f32 v[58:59], v[58:59], v[62:63]
	v_pk_mul_f32 v[48:49], v[48:49], v[52:53]
	v_pk_mul_f32 v[50:51], v[50:51], v[54:55]
	v_cvt_pk_bf16_f32 v56, v56, v57
	v_cvt_pk_bf16_f32 v57, v58, v59
	v_cvt_pk_bf16_f32 v58, v48, v49
	v_cvt_pk_bf16_f32 v59, v50, v51
	global_store_dwordx4 v[158:159], v[56:59], off sc1
	v_pk_mul_f32 v[160:161], v[44:45], v[168:169]
	v_pk_mul_f32 v[162:163], v[46:47], v[168:169]
	v_pk_mul_f32 v[164:165], v[36:37], v[168:169]
	v_pk_mul_f32 v[166:167], v[38:39], v[168:169]
	v_exp_f32_e32 v160, v160
	v_exp_f32_e32 v161, v161
	v_exp_f32_e32 v162, v162
	v_exp_f32_e32 v163, v163
	v_exp_f32_e32 v164, v164
	v_exp_f32_e32 v165, v165
	v_exp_f32_e32 v166, v166
	v_exp_f32_e32 v167, v167
	v_pk_add_f32 v[160:161], v[160:161], v[170:171]
	v_pk_add_f32 v[162:163], v[162:163], v[170:171]
	v_pk_add_f32 v[164:165], v[164:165], v[170:171]
	v_pk_add_f32 v[166:167], v[166:167], v[170:171]
	v_rcp_f32_e32 v160, v160
	v_rcp_f32_e32 v161, v161
	v_rcp_f32_e32 v162, v162
	v_rcp_f32_e32 v163, v163
	v_rcp_f32_e32 v164, v164
	v_rcp_f32_e32 v165, v165
	v_rcp_f32_e32 v166, v166
	v_rcp_f32_e32 v167, v167
	v_add_u32_e32 v158, 0x90, v156
	v_mad_i64_i32 v[158:159], s[18:19], v158, s73, v[152:153]
	v_pk_mul_f32 v[44:45], v[44:45], v[160:161]
	v_pk_mul_f32 v[46:47], v[46:47], v[162:163]
	v_pk_mul_f32 v[36:37], v[36:37], v[164:165]
	v_pk_mul_f32 v[38:39], v[38:39], v[166:167]
	v_pk_mul_f32 v[40:41], v[40:41], v[44:45]
	v_pk_mul_f32 v[42:43], v[42:43], v[46:47]
	v_pk_mul_f32 v[32:33], v[32:33], v[36:37]
	v_pk_mul_f32 v[34:35], v[34:35], v[38:39]
	v_cvt_pk_bf16_f32 v40, v40, v41
	v_cvt_pk_bf16_f32 v41, v42, v43
	v_cvt_pk_bf16_f32 v42, v32, v33
	v_cvt_pk_bf16_f32 v43, v34, v35
	global_store_dwordx4 v[158:159], v[40:43], off sc1
	v_pk_mul_f32 v[160:161], v[28:29], v[168:169]
	v_pk_mul_f32 v[162:163], v[30:31], v[168:169]
	v_pk_mul_f32 v[164:165], v[20:21], v[168:169]
	v_pk_mul_f32 v[166:167], v[22:23], v[168:169]
	v_exp_f32_e32 v160, v160
	v_exp_f32_e32 v161, v161
	v_exp_f32_e32 v162, v162
	v_exp_f32_e32 v163, v163
	v_exp_f32_e32 v164, v164
	v_exp_f32_e32 v165, v165
	v_exp_f32_e32 v166, v166
	v_exp_f32_e32 v167, v167
	v_pk_add_f32 v[160:161], v[160:161], v[170:171]
	v_pk_add_f32 v[162:163], v[162:163], v[170:171]
	v_pk_add_f32 v[164:165], v[164:165], v[170:171]
	v_pk_add_f32 v[166:167], v[166:167], v[170:171]
	v_rcp_f32_e32 v160, v160
	v_rcp_f32_e32 v161, v161
	v_rcp_f32_e32 v162, v162
	v_rcp_f32_e32 v163, v163
	v_rcp_f32_e32 v164, v164
	v_rcp_f32_e32 v165, v165
	v_rcp_f32_e32 v166, v166
	v_rcp_f32_e32 v167, v167
	v_add_u32_e32 v158, 0xa0, v156
	v_mad_i64_i32 v[158:159], s[18:19], v158, s73, v[152:153]
	v_pk_mul_f32 v[28:29], v[28:29], v[160:161]
	v_pk_mul_f32 v[30:31], v[30:31], v[162:163]
	v_pk_mul_f32 v[20:21], v[20:21], v[164:165]
	v_pk_mul_f32 v[22:23], v[22:23], v[166:167]
	v_pk_mul_f32 v[24:25], v[24:25], v[28:29]
	v_pk_mul_f32 v[26:27], v[26:27], v[30:31]
	v_pk_mul_f32 v[16:17], v[16:17], v[20:21]
	v_pk_mul_f32 v[18:19], v[18:19], v[22:23]
	v_cvt_pk_bf16_f32 v24, v24, v25
	v_cvt_pk_bf16_f32 v25, v26, v27
	v_cvt_pk_bf16_f32 v26, v16, v17
	v_cvt_pk_bf16_f32 v27, v18, v19
	global_store_dwordx4 v[158:159], v[24:27], off sc1
	v_pk_mul_f32 v[160:161], v[12:13], v[168:169]
	v_pk_mul_f32 v[162:163], v[14:15], v[168:169]
	v_pk_mul_f32 v[164:165], v[4:5], v[168:169]
	v_pk_mul_f32 v[166:167], v[6:7], v[168:169]
	v_exp_f32_e32 v160, v160
	v_exp_f32_e32 v161, v161
	v_exp_f32_e32 v162, v162
	v_exp_f32_e32 v163, v163
	v_exp_f32_e32 v164, v164
	v_exp_f32_e32 v165, v165
	v_exp_f32_e32 v166, v166
	v_exp_f32_e32 v167, v167
	v_pk_add_f32 v[160:161], v[160:161], v[170:171]
	v_pk_add_f32 v[162:163], v[162:163], v[170:171]
	v_pk_add_f32 v[164:165], v[164:165], v[170:171]
	v_pk_add_f32 v[166:167], v[166:167], v[170:171]
	v_rcp_f32_e32 v160, v160
	v_rcp_f32_e32 v161, v161
	v_rcp_f32_e32 v162, v162
	v_rcp_f32_e32 v163, v163
	v_rcp_f32_e32 v164, v164
	v_rcp_f32_e32 v165, v165
	v_rcp_f32_e32 v166, v166
	v_rcp_f32_e32 v167, v167
	v_add_u32_e32 v158, 0xb0, v156
	v_mad_i64_i32 v[158:159], s[18:19], v158, s73, v[152:153]
	v_pk_mul_f32 v[12:13], v[12:13], v[160:161]
	v_pk_mul_f32 v[14:15], v[14:15], v[162:163]
	v_pk_mul_f32 v[4:5], v[4:5], v[164:165]
	v_pk_mul_f32 v[6:7], v[6:7], v[166:167]
	v_pk_mul_f32 v[8:9], v[8:9], v[12:13]
	v_pk_mul_f32 v[10:11], v[10:11], v[14:15]
	v_pk_mul_f32 v[0:1], v[0:1], v[4:5]
	v_pk_mul_f32 v[2:3], v[2:3], v[6:7]
	v_cvt_pk_bf16_f32 v8, v8, v9
	v_cvt_pk_bf16_f32 v9, v10, v11
	v_cvt_pk_bf16_f32 v10, v0, v1
	v_cvt_pk_bf16_f32 v11, v2, v3
	global_store_dwordx4 v[158:159], v[8:11], off sc1
	s_mov_b64 s[18:19], s[10:11]
	s_cbranch_vccz .LBB0_1101
	s_waitcnt vmcnt(0)
	s_cmpk_gt_u32 s14, 0xff
	s_cbranch_scc1 .LBB0_1108
	s_barrier
